# final RMSNorm: gamma hoisted out of row loop, 4 rows of loads in flight with counted vmcnt; plus pool and x-conversion rewrites
# baseline (speedup 1.0000x reference)
.LBB0_967:
	v_mov_b32_e32 v2, v1
	v_readlane_b32 s0, v242, 10
	s_lshl_b32 s3, s0, 3
	v_ashrrev_i32_e32 v8, 6, v2
	s_waitcnt vmcnt(25)
	v_add_u32_e32 v14, s3, v8
	s_movk_i32 s0, 0x2000
	v_cmp_gt_i32_e32 vcc, s0, v14
	s_and_saveexec_b64 s[0:1], vcc
	s_cbranch_execz .LBB0_970
	v_readlane_b32 s2, v242, 2
	v_readlane_b32 s3, v242, 10
	v_readfirstlane_b32 s4, v1
	v_and_b32_e32 v15, 63, v1
	v_lshlrev_b32_e32 v3, 5, v15
	v_lshlrev_b32_e32 v4, 4, v15
	v_mov_b32_e32 v5, 0
	v_mov_b32_e32 v136, 0x358637bd
	s_mov_b32 s6, 0x800000
	s_lshr_b32 s4, s4, 6
	s_lshl_b32 s3, s3, 3
	s_add_u32 s3, s3, s4
	s_lshl_b32 s2, s2, 13
	s_add_u32 s12, s2, s3
	s_add_u32 s13, s2, 0x2000
	s_lshl_b32 s14, s33, 3
	s_add_u32 s98, s8, 0x1000
	s_addc_u32 s99, s9, 0
	global_load_dwordx4 v[16:19], v3, s[8:9]
	global_load_dwordx4 v[20:23], v3, s[8:9] offset:16
	global_load_dwordx4 v[24:27], v3, s[8:9] offset:2048
	global_load_dwordx4 v[28:31], v3, s[8:9] offset:2064
	global_load_dwordx4 v[32:35], v3, s[98:99]
	global_load_dwordx4 v[36:39], v3, s[98:99] offset:16
	global_load_dwordx4 v[40:43], v3, s[98:99] offset:2048
	global_load_dwordx4 v[44:47], v3, s[98:99] offset:2064
	s_add_u32 s16, s84, 0x3840000
	s_addc_u32 s17, s85, 0
	s_add_u32 s18, s84, 0x4000000
	s_addc_u32 s19, s85, 0
.Lfn_loop:
	s_cmp_ge_u32 s12, s13
	s_cbranch_scc1 .Lfn_done
	s_add_u32 s26, s12, s14
	s_add_u32 s27, s26, s14
	s_add_u32 s28, s27, s14
	s_cmp_ge_u32 s28, s13
	s_cbranch_scc1 .Lfn_single
	s_lshl_b32 s5, s12, 2
	s_add_u32 s22, s16, s5
	s_addc_u32 s23, s17, 0
	global_load_dword v112, v5, s[22:23]
	s_lshl_b32 s5, s12, 12
	s_add_u32 s22, s18, s5
	s_addc_u32 s23, s19, 0
	global_load_dwordx4 v[48:51], v4, s[22:23]
	global_load_dwordx4 v[52:55], v4, s[22:23] offset:1024
	global_load_dwordx4 v[56:59], v4, s[22:23] offset:2048
	global_load_dwordx4 v[60:63], v4, s[22:23] offset:3072
	s_lshl_b32 s5, s26, 2
	s_add_u32 s22, s16, s5
	s_addc_u32 s23, s17, 0
	global_load_dword v113, v5, s[22:23]
	s_lshl_b32 s5, s26, 12
	s_add_u32 s22, s18, s5
	s_addc_u32 s23, s19, 0
	global_load_dwordx4 v[64:67], v4, s[22:23]
	global_load_dwordx4 v[68:71], v4, s[22:23] offset:1024
	global_load_dwordx4 v[72:75], v4, s[22:23] offset:2048
	global_load_dwordx4 v[76:79], v4, s[22:23] offset:3072
	s_lshl_b32 s5, s27, 2
	s_add_u32 s22, s16, s5
	s_addc_u32 s23, s17, 0
	global_load_dword v114, v5, s[22:23]
	s_lshl_b32 s5, s27, 12
	s_add_u32 s22, s18, s5
	s_addc_u32 s23, s19, 0
	global_load_dwordx4 v[80:83], v4, s[22:23]
	global_load_dwordx4 v[84:87], v4, s[22:23] offset:1024
	global_load_dwordx4 v[88:91], v4, s[22:23] offset:2048
	global_load_dwordx4 v[92:95], v4, s[22:23] offset:3072
	s_lshl_b32 s5, s28, 2
	s_add_u32 s22, s16, s5
	s_addc_u32 s23, s17, 0
	global_load_dword v115, v5, s[22:23]
	s_lshl_b32 s5, s28, 12
	s_add_u32 s22, s18, s5
	s_addc_u32 s23, s19, 0
	global_load_dwordx4 v[96:99], v4, s[22:23]
	global_load_dwordx4 v[100:103], v4, s[22:23] offset:1024
	global_load_dwordx4 v[104:107], v4, s[22:23] offset:2048
	global_load_dwordx4 v[108:111], v4, s[22:23] offset:3072
	s_waitcnt vmcnt(15)
	s_lshl_b32 s5, s12, 13
	s_add_u32 s22, s10, s5
	s_addc_u32 s23, s11, 0
	s_add_u32 s24, s22, 0x1000
	s_addc_u32 s25, s23, 0
	v_fmamk_f32 v116, v112, 0x3a000000, v136
	v_mul_f32_e32 v117, 0x4b800000, v116
	v_cmp_gt_f32_e32 vcc, s6, v116
	s_nop 1
	v_cndmask_b32_e32 v116, v116, v117, vcc
	v_rsq_f32_e32 v116, v116
	s_nop 0
	v_mul_f32_e32 v117, 0x45800000, v116
	v_cndmask_b32_e32 v116, v116, v117, vcc
	v_lshlrev_b32_e32 v118, 16, v48
	v_and_b32_e32 v119, 0xffff0000, v48
	v_lshlrev_b32_e32 v120, 16, v49
	v_and_b32_e32 v121, 0xffff0000, v49
	v_lshlrev_b32_e32 v122, 16, v50
	v_and_b32_e32 v123, 0xffff0000, v50
	v_lshlrev_b32_e32 v124, 16, v51
	v_and_b32_e32 v125, 0xffff0000, v51
	v_pk_mul_f32 v[118:119], v[116:117], v[118:119] op_sel_hi:[0,1]
	v_pk_mul_f32 v[120:121], v[116:117], v[120:121] op_sel_hi:[0,1]
	v_pk_mul_f32 v[122:123], v[116:117], v[122:123] op_sel_hi:[0,1]
	v_pk_mul_f32 v[124:125], v[116:117], v[124:125] op_sel_hi:[0,1]
	v_pk_mul_f32 v[128:129], v[16:17], v[118:119]
	v_pk_mul_f32 v[130:131], v[18:19], v[120:121]
	v_pk_mul_f32 v[132:133], v[20:21], v[122:123]
	v_pk_mul_f32 v[134:135], v[22:23], v[124:125]
	global_store_dwordx4 v3, v[128:131], s[22:23] nt
	global_store_dwordx4 v3, v[132:135], s[22:23] offset:16 nt
	v_lshlrev_b32_e32 v118, 16, v52
	v_and_b32_e32 v119, 0xffff0000, v52
	v_lshlrev_b32_e32 v120, 16, v53
	v_and_b32_e32 v121, 0xffff0000, v53
	v_lshlrev_b32_e32 v122, 16, v54
	v_and_b32_e32 v123, 0xffff0000, v54
	v_lshlrev_b32_e32 v124, 16, v55
	v_and_b32_e32 v125, 0xffff0000, v55
	v_pk_mul_f32 v[118:119], v[116:117], v[118:119] op_sel_hi:[0,1]
	v_pk_mul_f32 v[120:121], v[116:117], v[120:121] op_sel_hi:[0,1]
	v_pk_mul_f32 v[122:123], v[116:117], v[122:123] op_sel_hi:[0,1]
	v_pk_mul_f32 v[124:125], v[116:117], v[124:125] op_sel_hi:[0,1]
	v_pk_mul_f32 v[128:129], v[24:25], v[118:119]
	v_pk_mul_f32 v[130:131], v[26:27], v[120:121]
	v_pk_mul_f32 v[132:133], v[28:29], v[122:123]
	v_pk_mul_f32 v[134:135], v[30:31], v[124:125]
	global_store_dwordx4 v3, v[128:131], s[22:23] offset:2048 nt
	global_store_dwordx4 v3, v[132:135], s[22:23] offset:2064 nt
	v_lshlrev_b32_e32 v118, 16, v56
	v_and_b32_e32 v119, 0xffff0000, v56
	v_lshlrev_b32_e32 v120, 16, v57
	v_and_b32_e32 v121, 0xffff0000, v57
	v_lshlrev_b32_e32 v122, 16, v58
	v_and_b32_e32 v123, 0xffff0000, v58
	v_lshlrev_b32_e32 v124, 16, v59
	v_and_b32_e32 v125, 0xffff0000, v59
	v_pk_mul_f32 v[118:119], v[116:117], v[118:119] op_sel_hi:[0,1]
	v_pk_mul_f32 v[120:121], v[116:117], v[120:121] op_sel_hi:[0,1]
	v_pk_mul_f32 v[122:123], v[116:117], v[122:123] op_sel_hi:[0,1]
	v_pk_mul_f32 v[124:125], v[116:117], v[124:125] op_sel_hi:[0,1]
	v_pk_mul_f32 v[128:129], v[32:33], v[118:119]
	v_pk_mul_f32 v[130:131], v[34:35], v[120:121]
	v_pk_mul_f32 v[132:133], v[36:37], v[122:123]
	v_pk_mul_f32 v[134:135], v[38:39], v[124:125]
	global_store_dwordx4 v3, v[128:131], s[24:25] nt
	global_store_dwordx4 v3, v[132:135], s[24:25] offset:16 nt
	v_lshlrev_b32_e32 v118, 16, v60
	v_and_b32_e32 v119, 0xffff0000, v60
	v_lshlrev_b32_e32 v120, 16, v61
	v_and_b32_e32 v121, 0xffff0000, v61
	v_lshlrev_b32_e32 v122, 16, v62
	v_and_b32_e32 v123, 0xffff0000, v62
	v_lshlrev_b32_e32 v124, 16, v63
	v_and_b32_e32 v125, 0xffff0000, v63
	v_pk_mul_f32 v[118:119], v[116:117], v[118:119] op_sel_hi:[0,1]
	v_pk_mul_f32 v[120:121], v[116:117], v[120:121] op_sel_hi:[0,1]
	v_pk_mul_f32 v[122:123], v[116:117], v[122:123] op_sel_hi:[0,1]
	v_pk_mul_f32 v[124:125], v[116:117], v[124:125] op_sel_hi:[0,1]
	v_pk_mul_f32 v[128:129], v[40:41], v[118:119]
	v_pk_mul_f32 v[130:131], v[42:43], v[120:121]
	v_pk_mul_f32 v[132:133], v[44:45], v[122:123]
	v_pk_mul_f32 v[134:135], v[46:47], v[124:125]
	global_store_dwordx4 v3, v[128:131], s[24:25] offset:2048 nt
	global_store_dwordx4 v3, v[132:135], s[24:25] offset:2064 nt
	s_waitcnt vmcnt(18)
	s_lshl_b32 s5, s26, 13
	s_add_u32 s22, s10, s5
	s_addc_u32 s23, s11, 0
	s_add_u32 s24, s22, 0x1000
	s_addc_u32 s25, s23, 0
	v_fmamk_f32 v116, v113, 0x3a000000, v136
	v_mul_f32_e32 v117, 0x4b800000, v116
	v_cmp_gt_f32_e32 vcc, s6, v116
	s_nop 1
	v_cndmask_b32_e32 v116, v116, v117, vcc
	v_rsq_f32_e32 v116, v116
	s_nop 0
	v_mul_f32_e32 v117, 0x45800000, v116
	v_cndmask_b32_e32 v116, v116, v117, vcc
	v_lshlrev_b32_e32 v118, 16, v64
	v_and_b32_e32 v119, 0xffff0000, v64
	v_lshlrev_b32_e32 v120, 16, v65
	v_and_b32_e32 v121, 0xffff0000, v65
	v_lshlrev_b32_e32 v122, 16, v66
	v_and_b32_e32 v123, 0xffff0000, v66
	v_lshlrev_b32_e32 v124, 16, v67
	v_and_b32_e32 v125, 0xffff0000, v67
	v_pk_mul_f32 v[118:119], v[116:117], v[118:119] op_sel_hi:[0,1]
	v_pk_mul_f32 v[120:121], v[116:117], v[120:121] op_sel_hi:[0,1]
	v_pk_mul_f32 v[122:123], v[116:117], v[122:123] op_sel_hi:[0,1]
	v_pk_mul_f32 v[124:125], v[116:117], v[124:125] op_sel_hi:[0,1]
	v_pk_mul_f32 v[128:129], v[16:17], v[118:119]
	v_pk_mul_f32 v[130:131], v[18:19], v[120:121]
	v_pk_mul_f32 v[132:133], v[20:21], v[122:123]
	v_pk_mul_f32 v[134:135], v[22:23], v[124:125]
	global_store_dwordx4 v3, v[128:131], s[22:23] nt
	global_store_dwordx4 v3, v[132:135], s[22:23] offset:16 nt
	v_lshlrev_b32_e32 v118, 16, v68
	v_and_b32_e32 v119, 0xffff0000, v68
	v_lshlrev_b32_e32 v120, 16, v69
	v_and_b32_e32 v121, 0xffff0000, v69
	v_lshlrev_b32_e32 v122, 16, v70
	v_and_b32_e32 v123, 0xffff0000, v70
	v_lshlrev_b32_e32 v124, 16, v71
	v_and_b32_e32 v125, 0xffff0000, v71
	v_pk_mul_f32 v[118:119], v[116:117], v[118:119] op_sel_hi:[0,1]
	v_pk_mul_f32 v[120:121], v[116:117], v[120:121] op_sel_hi:[0,1]
	v_pk_mul_f32 v[122:123], v[116:117], v[122:123] op_sel_hi:[0,1]
	v_pk_mul_f32 v[124:125], v[116:117], v[124:125] op_sel_hi:[0,1]
	v_pk_mul_f32 v[128:129], v[24:25], v[118:119]
	v_pk_mul_f32 v[130:131], v[26:27], v[120:121]
	v_pk_mul_f32 v[132:133], v[28:29], v[122:123]
	v_pk_mul_f32 v[134:135], v[30:31], v[124:125]
	global_store_dwordx4 v3, v[128:131], s[22:23] offset:2048 nt
	global_store_dwordx4 v3, v[132:135], s[22:23] offset:2064 nt
	v_lshlrev_b32_e32 v118, 16, v72
	v_and_b32_e32 v119, 0xffff0000, v72
	v_lshlrev_b32_e32 v120, 16, v73
	v_and_b32_e32 v121, 0xffff0000, v73
	v_lshlrev_b32_e32 v122, 16, v74
	v_and_b32_e32 v123, 0xffff0000, v74
	v_lshlrev_b32_e32 v124, 16, v75
	v_and_b32_e32 v125, 0xffff0000, v75
	v_pk_mul_f32 v[118:119], v[116:117], v[118:119] op_sel_hi:[0,1]
	v_pk_mul_f32 v[120:121], v[116:117], v[120:121] op_sel_hi:[0,1]
	v_pk_mul_f32 v[122:123], v[116:117], v[122:123] op_sel_hi:[0,1]
	v_pk_mul_f32 v[124:125], v[116:117], v[124:125] op_sel_hi:[0,1]
	v_pk_mul_f32 v[128:129], v[32:33], v[118:119]
	v_pk_mul_f32 v[130:131], v[34:35], v[120:121]
	v_pk_mul_f32 v[132:133], v[36:37], v[122:123]
	v_pk_mul_f32 v[134:135], v[38:39], v[124:125]
	global_store_dwordx4 v3, v[128:131], s[24:25] nt
	global_store_dwordx4 v3, v[132:135], s[24:25] offset:16 nt
	v_lshlrev_b32_e32 v118, 16, v76
	v_and_b32_e32 v119, 0xffff0000, v76
	v_lshlrev_b32_e32 v120, 16, v77
	v_and_b32_e32 v121, 0xffff0000, v77
	v_lshlrev_b32_e32 v122, 16, v78
	v_and_b32_e32 v123, 0xffff0000, v78
	v_lshlrev_b32_e32 v124, 16, v79
	v_and_b32_e32 v125, 0xffff0000, v79
	v_pk_mul_f32 v[118:119], v[116:117], v[118:119] op_sel_hi:[0,1]
	v_pk_mul_f32 v[120:121], v[116:117], v[120:121] op_sel_hi:[0,1]
	v_pk_mul_f32 v[122:123], v[116:117], v[122:123] op_sel_hi:[0,1]
	v_pk_mul_f32 v[124:125], v[116:117], v[124:125] op_sel_hi:[0,1]
	v_pk_mul_f32 v[128:129], v[40:41], v[118:119]
	v_pk_mul_f32 v[130:131], v[42:43], v[120:121]
	v_pk_mul_f32 v[132:133], v[44:45], v[122:123]
	v_pk_mul_f32 v[134:135], v[46:47], v[124:125]
	global_store_dwordx4 v3, v[128:131], s[24:25] offset:2048 nt
	global_store_dwordx4 v3, v[132:135], s[24:25] offset:2064 nt
	s_waitcnt vmcnt(21)
	s_lshl_b32 s5, s27, 13
	s_add_u32 s22, s10, s5
	s_addc_u32 s23, s11, 0
	s_add_u32 s24, s22, 0x1000
	s_addc_u32 s25, s23, 0
	v_fmamk_f32 v116, v114, 0x3a000000, v136
	v_mul_f32_e32 v117, 0x4b800000, v116
	v_cmp_gt_f32_e32 vcc, s6, v116
	s_nop 1
	v_cndmask_b32_e32 v116, v116, v117, vcc
	v_rsq_f32_e32 v116, v116
	s_nop 0
	v_mul_f32_e32 v117, 0x45800000, v116
	v_cndmask_b32_e32 v116, v116, v117, vcc
	v_lshlrev_b32_e32 v118, 16, v80
	v_and_b32_e32 v119, 0xffff0000, v80
	v_lshlrev_b32_e32 v120, 16, v81
	v_and_b32_e32 v121, 0xffff0000, v81
	v_lshlrev_b32_e32 v122, 16, v82
	v_and_b32_e32 v123, 0xffff0000, v82
	v_lshlrev_b32_e32 v124, 16, v83
	v_and_b32_e32 v125, 0xffff0000, v83
	v_pk_mul_f32 v[118:119], v[116:117], v[118:119] op_sel_hi:[0,1]
	v_pk_mul_f32 v[120:121], v[116:117], v[120:121] op_sel_hi:[0,1]
	v_pk_mul_f32 v[122:123], v[116:117], v[122:123] op_sel_hi:[0,1]
	v_pk_mul_f32 v[124:125], v[116:117], v[124:125] op_sel_hi:[0,1]
	v_pk_mul_f32 v[128:129], v[16:17], v[118:119]
	v_pk_mul_f32 v[130:131], v[18:19], v[120:121]
	v_pk_mul_f32 v[132:133], v[20:21], v[122:123]
	v_pk_mul_f32 v[134:135], v[22:23], v[124:125]
	global_store_dwordx4 v3, v[128:131], s[22:23] nt
	global_store_dwordx4 v3, v[132:135], s[22:23] offset:16 nt
	v_lshlrev_b32_e32 v118, 16, v84
	v_and_b32_e32 v119, 0xffff0000, v84
	v_lshlrev_b32_e32 v120, 16, v85
	v_and_b32_e32 v121, 0xffff0000, v85
	v_lshlrev_b32_e32 v122, 16, v86
	v_and_b32_e32 v123, 0xffff0000, v86
	v_lshlrev_b32_e32 v124, 16, v87
	v_and_b32_e32 v125, 0xffff0000, v87
	v_pk_mul_f32 v[118:119], v[116:117], v[118:119] op_sel_hi:[0,1]
	v_pk_mul_f32 v[120:121], v[116:117], v[120:121] op_sel_hi:[0,1]
	v_pk_mul_f32 v[122:123], v[116:117], v[122:123] op_sel_hi:[0,1]
	v_pk_mul_f32 v[124:125], v[116:117], v[124:125] op_sel_hi:[0,1]
	v_pk_mul_f32 v[128:129], v[24:25], v[118:119]
	v_pk_mul_f32 v[130:131], v[26:27], v[120:121]
	v_pk_mul_f32 v[132:133], v[28:29], v[122:123]
	v_pk_mul_f32 v[134:135], v[30:31], v[124:125]
	global_store_dwordx4 v3, v[128:131], s[22:23] offset:2048 nt
	global_store_dwordx4 v3, v[132:135], s[22:23] offset:2064 nt
	v_lshlrev_b32_e32 v118, 16, v88
	v_and_b32_e32 v119, 0xffff0000, v88
	v_lshlrev_b32_e32 v120, 16, v89
	v_and_b32_e32 v121, 0xffff0000, v89
	v_lshlrev_b32_e32 v122, 16, v90
	v_and_b32_e32 v123, 0xffff0000, v90
	v_lshlrev_b32_e32 v124, 16, v91
	v_and_b32_e32 v125, 0xffff0000, v91
	v_pk_mul_f32 v[118:119], v[116:117], v[118:119] op_sel_hi:[0,1]
	v_pk_mul_f32 v[120:121], v[116:117], v[120:121] op_sel_hi:[0,1]
	v_pk_mul_f32 v[122:123], v[116:117], v[122:123] op_sel_hi:[0,1]
	v_pk_mul_f32 v[124:125], v[116:117], v[124:125] op_sel_hi:[0,1]
	v_pk_mul_f32 v[128:129], v[32:33], v[118:119]
	v_pk_mul_f32 v[130:131], v[34:35], v[120:121]
	v_pk_mul_f32 v[132:133], v[36:37], v[122:123]
	v_pk_mul_f32 v[134:135], v[38:39], v[124:125]
	global_store_dwordx4 v3, v[128:131], s[24:25] nt
	global_store_dwordx4 v3, v[132:135], s[24:25] offset:16 nt
	v_lshlrev_b32_e32 v118, 16, v92
	v_and_b32_e32 v119, 0xffff0000, v92
	v_lshlrev_b32_e32 v120, 16, v93
	v_and_b32_e32 v121, 0xffff0000, v93
	v_lshlrev_b32_e32 v122, 16, v94
	v_and_b32_e32 v123, 0xffff0000, v94
	v_lshlrev_b32_e32 v124, 16, v95
	v_and_b32_e32 v125, 0xffff0000, v95
	v_pk_mul_f32 v[118:119], v[116:117], v[118:119] op_sel_hi:[0,1]
	v_pk_mul_f32 v[120:121], v[116:117], v[120:121] op_sel_hi:[0,1]
	v_pk_mul_f32 v[122:123], v[116:117], v[122:123] op_sel_hi:[0,1]
	v_pk_mul_f32 v[124:125], v[116:117], v[124:125] op_sel_hi:[0,1]
	v_pk_mul_f32 v[128:129], v[40:41], v[118:119]
	v_pk_mul_f32 v[130:131], v[42:43], v[120:121]
	v_pk_mul_f32 v[132:133], v[44:45], v[122:123]
	v_pk_mul_f32 v[134:135], v[46:47], v[124:125]
	global_store_dwordx4 v3, v[128:131], s[24:25] offset:2048 nt
	global_store_dwordx4 v3, v[132:135], s[24:25] offset:2064 nt
	s_waitcnt vmcnt(24)
	s_lshl_b32 s5, s28, 13
	s_add_u32 s22, s10, s5
	s_addc_u32 s23, s11, 0
	s_add_u32 s24, s22, 0x1000
	s_addc_u32 s25, s23, 0
	v_fmamk_f32 v116, v115, 0x3a000000, v136
	v_mul_f32_e32 v117, 0x4b800000, v116
	v_cmp_gt_f32_e32 vcc, s6, v116
	s_nop 1
	v_cndmask_b32_e32 v116, v116, v117, vcc
	v_rsq_f32_e32 v116, v116
	s_nop 0
	v_mul_f32_e32 v117, 0x45800000, v116
	v_cndmask_b32_e32 v116, v116, v117, vcc
	v_lshlrev_b32_e32 v118, 16, v96
	v_and_b32_e32 v119, 0xffff0000, v96
	v_lshlrev_b32_e32 v120, 16, v97
	v_and_b32_e32 v121, 0xffff0000, v97
	v_lshlrev_b32_e32 v122, 16, v98
	v_and_b32_e32 v123, 0xffff0000, v98
	v_lshlrev_b32_e32 v124, 16, v99
	v_and_b32_e32 v125, 0xffff0000, v99
	v_pk_mul_f32 v[118:119], v[116:117], v[118:119] op_sel_hi:[0,1]
	v_pk_mul_f32 v[120:121], v[116:117], v[120:121] op_sel_hi:[0,1]
	v_pk_mul_f32 v[122:123], v[116:117], v[122:123] op_sel_hi:[0,1]
	v_pk_mul_f32 v[124:125], v[116:117], v[124:125] op_sel_hi:[0,1]
	v_pk_mul_f32 v[128:129], v[16:17], v[118:119]
	v_pk_mul_f32 v[130:131], v[18:19], v[120:121]
	v_pk_mul_f32 v[132:133], v[20:21], v[122:123]
	v_pk_mul_f32 v[134:135], v[22:23], v[124:125]
	global_store_dwordx4 v3, v[128:131], s[22:23] nt
	global_store_dwordx4 v3, v[132:135], s[22:23] offset:16 nt
	v_lshlrev_b32_e32 v118, 16, v100
	v_and_b32_e32 v119, 0xffff0000, v100
	v_lshlrev_b32_e32 v120, 16, v101
	v_and_b32_e32 v121, 0xffff0000, v101
	v_lshlrev_b32_e32 v122, 16, v102
	v_and_b32_e32 v123, 0xffff0000, v102
	v_lshlrev_b32_e32 v124, 16, v103
	v_and_b32_e32 v125, 0xffff0000, v103
	v_pk_mul_f32 v[118:119], v[116:117], v[118:119] op_sel_hi:[0,1]
	v_pk_mul_f32 v[120:121], v[116:117], v[120:121] op_sel_hi:[0,1]
	v_pk_mul_f32 v[122:123], v[116:117], v[122:123] op_sel_hi:[0,1]
	v_pk_mul_f32 v[124:125], v[116:117], v[124:125] op_sel_hi:[0,1]
	v_pk_mul_f32 v[128:129], v[24:25], v[118:119]
	v_pk_mul_f32 v[130:131], v[26:27], v[120:121]
	v_pk_mul_f32 v[132:133], v[28:29], v[122:123]
	v_pk_mul_f32 v[134:135], v[30:31], v[124:125]
	global_store_dwordx4 v3, v[128:131], s[22:23] offset:2048 nt
	global_store_dwordx4 v3, v[132:135], s[22:23] offset:2064 nt
	v_lshlrev_b32_e32 v118, 16, v104
	v_and_b32_e32 v119, 0xffff0000, v104
	v_lshlrev_b32_e32 v120, 16, v105
	v_and_b32_e32 v121, 0xffff0000, v105
	v_lshlrev_b32_e32 v122, 16, v106
	v_and_b32_e32 v123, 0xffff0000, v106
	v_lshlrev_b32_e32 v124, 16, v107
	v_and_b32_e32 v125, 0xffff0000, v107
	v_pk_mul_f32 v[118:119], v[116:117], v[118:119] op_sel_hi:[0,1]
	v_pk_mul_f32 v[120:121], v[116:117], v[120:121] op_sel_hi:[0,1]
	v_pk_mul_f32 v[122:123], v[116:117], v[122:123] op_sel_hi:[0,1]
	v_pk_mul_f32 v[124:125], v[116:117], v[124:125] op_sel_hi:[0,1]
	v_pk_mul_f32 v[128:129], v[32:33], v[118:119]
	v_pk_mul_f32 v[130:131], v[34:35], v[120:121]
	v_pk_mul_f32 v[132:133], v[36:37], v[122:123]
	v_pk_mul_f32 v[134:135], v[38:39], v[124:125]
	global_store_dwordx4 v3, v[128:131], s[24:25] nt
	global_store_dwordx4 v3, v[132:135], s[24:25] offset:16 nt
	v_lshlrev_b32_e32 v118, 16, v108
	v_and_b32_e32 v119, 0xffff0000, v108
	v_lshlrev_b32_e32 v120, 16, v109
	v_and_b32_e32 v121, 0xffff0000, v109
	v_lshlrev_b32_e32 v122, 16, v110
	v_and_b32_e32 v123, 0xffff0000, v110
	v_lshlrev_b32_e32 v124, 16, v111
	v_and_b32_e32 v125, 0xffff0000, v111
	v_pk_mul_f32 v[118:119], v[116:117], v[118:119] op_sel_hi:[0,1]
	v_pk_mul_f32 v[120:121], v[116:117], v[120:121] op_sel_hi:[0,1]
	v_pk_mul_f32 v[122:123], v[116:117], v[122:123] op_sel_hi:[0,1]
	v_pk_mul_f32 v[124:125], v[116:117], v[124:125] op_sel_hi:[0,1]
	v_pk_mul_f32 v[128:129], v[40:41], v[118:119]
	v_pk_mul_f32 v[130:131], v[42:43], v[120:121]
	v_pk_mul_f32 v[132:133], v[44:45], v[122:123]
	v_pk_mul_f32 v[134:135], v[46:47], v[124:125]
	global_store_dwordx4 v3, v[128:131], s[24:25] offset:2048 nt
	global_store_dwordx4 v3, v[132:135], s[24:25] offset:2064 nt
	s_add_u32 s12, s28, s14
	s_branch .Lfn_loop
.Lfn_single:
	s_lshl_b32 s5, s12, 2
	s_add_u32 s22, s16, s5
	s_addc_u32 s23, s17, 0
	global_load_dword v112, v5, s[22:23]
	s_lshl_b32 s5, s12, 12
	s_add_u32 s22, s18, s5
	s_addc_u32 s23, s19, 0
	global_load_dwordx4 v[48:51], v4, s[22:23]
	global_load_dwordx4 v[52:55], v4, s[22:23] offset:1024
	global_load_dwordx4 v[56:59], v4, s[22:23] offset:2048
	global_load_dwordx4 v[60:63], v4, s[22:23] offset:3072
	s_waitcnt vmcnt(0)
	s_lshl_b32 s5, s12, 13
	s_add_u32 s22, s10, s5
	s_addc_u32 s23, s11, 0
	s_add_u32 s24, s22, 0x1000
	s_addc_u32 s25, s23, 0
	v_fmamk_f32 v116, v112, 0x3a000000, v136
	v_mul_f32_e32 v117, 0x4b800000, v116
	v_cmp_gt_f32_e32 vcc, s6, v116
	s_nop 1
	v_cndmask_b32_e32 v116, v116, v117, vcc
	v_rsq_f32_e32 v116, v116
	s_nop 0
	v_mul_f32_e32 v117, 0x45800000, v116
	v_cndmask_b32_e32 v116, v116, v117, vcc
	v_lshlrev_b32_e32 v118, 16, v48
	v_and_b32_e32 v119, 0xffff0000, v48
	v_lshlrev_b32_e32 v120, 16, v49
	v_and_b32_e32 v121, 0xffff0000, v49
	v_lshlrev_b32_e32 v122, 16, v50
	v_and_b32_e32 v123, 0xffff0000, v50
	v_lshlrev_b32_e32 v124, 16, v51
	v_and_b32_e32 v125, 0xffff0000, v51
	v_pk_mul_f32 v[118:119], v[116:117], v[118:119] op_sel_hi:[0,1]
	v_pk_mul_f32 v[120:121], v[116:117], v[120:121] op_sel_hi:[0,1]
	v_pk_mul_f32 v[122:123], v[116:117], v[122:123] op_sel_hi:[0,1]
	v_pk_mul_f32 v[124:125], v[116:117], v[124:125] op_sel_hi:[0,1]
	v_pk_mul_f32 v[128:129], v[16:17], v[118:119]
	v_pk_mul_f32 v[130:131], v[18:19], v[120:121]
	v_pk_mul_f32 v[132:133], v[20:21], v[122:123]
	v_pk_mul_f32 v[134:135], v[22:23], v[124:125]
	global_store_dwordx4 v3, v[128:131], s[22:23] nt
	global_store_dwordx4 v3, v[132:135], s[22:23] offset:16 nt
	v_lshlrev_b32_e32 v118, 16, v52
	v_and_b32_e32 v119, 0xffff0000, v52
	v_lshlrev_b32_e32 v120, 16, v53
	v_and_b32_e32 v121, 0xffff0000, v53
	v_lshlrev_b32_e32 v122, 16, v54
	v_and_b32_e32 v123, 0xffff0000, v54
	v_lshlrev_b32_e32 v124, 16, v55
	v_and_b32_e32 v125, 0xffff0000, v55
	v_pk_mul_f32 v[118:119], v[116:117], v[118:119] op_sel_hi:[0,1]
	v_pk_mul_f32 v[120:121], v[116:117], v[120:121] op_sel_hi:[0,1]
	v_pk_mul_f32 v[122:123], v[116:117], v[122:123] op_sel_hi:[0,1]
	v_pk_mul_f32 v[124:125], v[116:117], v[124:125] op_sel_hi:[0,1]
	v_pk_mul_f32 v[128:129], v[24:25], v[118:119]
	v_pk_mul_f32 v[130:131], v[26:27], v[120:121]
	v_pk_mul_f32 v[132:133], v[28:29], v[122:123]
	v_pk_mul_f32 v[134:135], v[30:31], v[124:125]
	global_store_dwordx4 v3, v[128:131], s[22:23] offset:2048 nt
	global_store_dwordx4 v3, v[132:135], s[22:23] offset:2064 nt
	v_lshlrev_b32_e32 v118, 16, v56
	v_and_b32_e32 v119, 0xffff0000, v56
	v_lshlrev_b32_e32 v120, 16, v57
	v_and_b32_e32 v121, 0xffff0000, v57
	v_lshlrev_b32_e32 v122, 16, v58
	v_and_b32_e32 v123, 0xffff0000, v58
	v_lshlrev_b32_e32 v124, 16, v59
	v_and_b32_e32 v125, 0xffff0000, v59
	v_pk_mul_f32 v[118:119], v[116:117], v[118:119] op_sel_hi:[0,1]
	v_pk_mul_f32 v[120:121], v[116:117], v[120:121] op_sel_hi:[0,1]
	v_pk_mul_f32 v[122:123], v[116:117], v[122:123] op_sel_hi:[0,1]
	v_pk_mul_f32 v[124:125], v[116:117], v[124:125] op_sel_hi:[0,1]
	v_pk_mul_f32 v[128:129], v[32:33], v[118:119]
	v_pk_mul_f32 v[130:131], v[34:35], v[120:121]
	v_pk_mul_f32 v[132:133], v[36:37], v[122:123]
	v_pk_mul_f32 v[134:135], v[38:39], v[124:125]
	global_store_dwordx4 v3, v[128:131], s[24:25] nt
	global_store_dwordx4 v3, v[132:135], s[24:25] offset:16 nt
	v_lshlrev_b32_e32 v118, 16, v60
	v_and_b32_e32 v119, 0xffff0000, v60
	v_lshlrev_b32_e32 v120, 16, v61
	v_and_b32_e32 v121, 0xffff0000, v61
	v_lshlrev_b32_e32 v122, 16, v62
	v_and_b32_e32 v123, 0xffff0000, v62
	v_lshlrev_b32_e32 v124, 16, v63
	v_and_b32_e32 v125, 0xffff0000, v63
	v_pk_mul_f32 v[118:119], v[116:117], v[118:119] op_sel_hi:[0,1]
	v_pk_mul_f32 v[120:121], v[116:117], v[120:121] op_sel_hi:[0,1]
	v_pk_mul_f32 v[122:123], v[116:117], v[122:123] op_sel_hi:[0,1]
	v_pk_mul_f32 v[124:125], v[116:117], v[124:125] op_sel_hi:[0,1]
	v_pk_mul_f32 v[128:129], v[40:41], v[118:119]
	v_pk_mul_f32 v[130:131], v[42:43], v[120:121]
	v_pk_mul_f32 v[132:133], v[44:45], v[122:123]
	v_pk_mul_f32 v[134:135], v[46:47], v[124:125]
	global_store_dwordx4 v3, v[128:131], s[24:25] offset:2048 nt
	global_store_dwordx4 v3, v[132:135], s[24:25] offset:2064 nt
	s_add_u32 s12, s12, s14
	s_branch .Lfn_loop
.Lfn_done:
.LBB0_970:
	s_or_b64 exec, exec, s[0:1]
	v_readlane_b32 s0, v242, 5
	s_cmpk_lg_i32 s0, 0x3039
	s_cbranch_scc1 .LBB0_982
	v_lshrrev_b32_e32 v2, 20, v0
	v_lshrrev_b32_e32 v0, 10, v0
	v_or_b32_e32 v0, v0, v2
	s_movk_i32 s0, 0x3ff
	v_and_or_b32 v0, v0, s0, v1
	v_cmp_eq_u32_e32 vcc, 0, v0
	s_barrier
	s_and_saveexec_b64 s[0:1], vcc
	s_cbranch_execz .LBB0_981
	v_readlane_b32 s2, v242, 0
	v_readlane_b32 s3, v242, 1
	buffer_wbl2 sc1
	s_waitcnt vmcnt(0)
	s_load_dwordx2 s[2:3], s[2:3], 0x58
	v_mov_b32_e32 v2, 0
	s_mov_b64 s[4:5], exec
	v_mbcnt_lo_u32_b32 v1, s4, 0
	v_mbcnt_hi_u32_b32 v1, s5, v1
	s_waitcnt lgkmcnt(0)
	global_load_dword v0, v2, s[2:3] offset:40
	v_cmp_eq_u32_e32 vcc, 0, v1
	s_and_saveexec_b64 s[6:7], vcc
	s_cbranch_execz .LBB0_974
	s_bcnt1_i32_b64 s4, s[4:5]
	v_mov_b32_e32 v3, s4
	global_atomic_add v3, v2, v3, s[2:3] offset:32 sc0
